# kv up-projection GEMM takes the unit list of CU c^128 so its extra unit does not stack on the CUs with the extra q up-projection unit
# baseline (speedup 1.0000x reference)
.LBB0_418:
	s_add_u32 s94, s96, 0x19000000
	s_addc_u32 s95, s97, 0
	v_readlane_b32 s0, v255, 2
	s_add_u32 s38, s96, 0x1fc00000
	s_mov_b32 s24, s0
	v_readlane_b32 s3, v255, 4
	s_addc_u32 s39, s97, 0
	v_mov_b32_e32 v0, v181
	s_xor_b32 s3, s3, 0x80
	s_cmpk_gt_i32 s3, 0x47f
	v_readfirstlane_b32 s4, v0
	v_readlane_b32 s1, v255, 3
	s_cbranch_scc1 .LBB0_432
	v_lshlrev_b32_e32 v1, 4, v0
	v_add_u32_e32 v2, 0x2000, v1
	v_ashrrev_i32_e32 v3, 31, v2
	v_lshrrev_b32_e32 v3, 22, v3
	v_add_u32_e32 v3, v2, v3
	v_ashrrev_i32_e32 v3, 10, v3
	v_mul_i32_i24_e32 v4, 0x400, v3
	v_sub_u32_e32 v2, v2, v4
	v_lshrrev_b32_e32 v4, 4, v2
	v_bitop3_b32 v2, v4, v2, 32 bitop3:0x6c
	v_readlane_b32 s0, v255, 13
	v_ashrrev_i32_e32 v4, 31, v2
	s_add_u32 s25, s96, 0x10000200
	v_readlane_b32 s1, v255, 14
	v_lshrrev_b32_e32 v4, 26, v4
	s_addc_u32 s26, s97, 0
	s_lshl_b64 s[0:1], s[0:1], 19
	v_add_u32_e32 v4, v2, v4
	v_lshlrev_b32_e32 v6, 3, v3
	s_add_u32 s0, s96, s0
	v_ashrrev_i32_e32 v5, 6, v4
	v_and_b32_e32 v6, -16, v6
	v_and_b32_e32 v4, 0xc0, v4
	s_addc_u32 s1, s97, s1
	v_add_u32_e32 v6, v5, v6
	v_sub_u32_e32 v2, v2, v4
	s_add_u32 s27, s0, 0xa000000
	v_and_b32_e32 v5, 3, v5
	s_mov_b32 s0, 0xffffe0
	v_lshrrev_b32_e32 v7, 2, v6
	v_lshlrev_b32_e32 v8, 1, v6
	v_lshlrev_b32_e32 v3, 5, v3
	v_ashrrev_i16_sdwa v2, v219, sext(v2) dst_sel:DWORD dst_unused:UNUSED_PAD src0_sel:DWORD src1_sel:BYTE_0
	v_and_or_b32 v5, v6, s0, v5
	v_and_b32_e32 v7, 4, v7
	v_and_b32_e32 v8, 24, v8
	v_and_b32_e32 v3, 32, v3
	v_bfe_i32 v2, v2, 0, 16
	v_or3_b32 v5, v5, v7, v8
	v_add_lshl_u32 v2, v3, v2, 1
	v_lshl_add_u32 v128, v5, 8, v2
	v_lshl_add_u32 v130, v6, 10, v2
	v_bfe_i32 v2, v0, 27, 1
	v_lshrrev_b32_e32 v2, 22, v2
	v_add_u32_e32 v2, v1, v2
	v_and_b32_e32 v2, 0xfffffc00, v2
	v_sub_u32_e32 v1, v1, v2
	v_lshrrev_b32_e32 v2, 4, v1
	v_ashrrev_i32_e32 v4, 31, v0
	v_bitop3_b32 v1, v2, v1, 32 bitop3:0x6c
	v_lshrrev_b32_e32 v4, 26, v4
	v_ashrrev_i32_e32 v2, 31, v1
	v_add_u32_e32 v4, v0, v4
	v_lshrrev_b32_e32 v2, 26, v2
	v_ashrrev_i32_e32 v4, 6, v4
	v_add_u32_e32 v2, v1, v2
	v_lshlrev_b32_e32 v5, 3, v4
	v_ashrrev_i32_e32 v3, 6, v2
	v_and_b32_e32 v5, -16, v5
	s_addc_u32 s28, s1, 0
	v_add_u32_e32 v5, v3, v5
	v_and_b32_e32 v3, 3, v3
	s_ashr_i32 s7, s3, 31
	v_and_or_b32 v3, v5, s0, v3
	s_lshr_b32 s0, s7, 29
	s_add_i32 s0, s3, s0
	s_ashr_i32 s5, s4, 6
	s_ashr_i32 s1, s0, 3
	s_and_b32 s0, s0, -8
	s_ashr_i32 s6, s4, 8
	s_lshl_b32 s29, s5, 10
	s_sub_i32 s0, s3, s0
	s_cmp_lt_i32 s0, 0
	s_movk_i32 s2, 0x91
	s_cselect_b32 s2, s2, 0x90
	s_mul_i32 s0, s0, s2
	s_add_i32 s0, s0, s1
	s_ashr_i32 s1, s0, 31
	s_lshr_b32 s1, s1, 26
	s_add_i32 s1, s0, s1
	s_ashr_i32 s2, s1, 6
	s_and_b32 s1, s1, 0xffc0
	s_sub_i32 s0, s0, s1
	s_bfe_i32 s1, s0, 0x80000
	s_bfe_u32 s1, s1, 0x3000c
	s_add_i32 s1, s0, s1
	s_lshl_b32 s8, s2, 3
	s_bfe_i32 s2, s1, 0x80000
	s_and_b32 s1, s1, 0xf8
	s_sub_i32 s0, s0, s1
	s_sext_i32_i16 s2, s2
	s_sext_i32_i8 s0, s0
	v_and_b32_e32 v2, 0xc0, v2
	s_lshr_b32 s2, s2, 3
	s_add_i32 s16, s8, s0
	v_sub_u32_e32 v1, v1, v2
	s_ashr_i32 s17, s16, 31
	s_bfe_i64 s[8:9], s[2:3], 0x100000
	v_lshrrev_b32_e32 v6, 2, v5
	v_lshlrev_b32_e32 v7, 1, v5
	v_lshlrev_b32_e32 v4, 5, v4
	v_ashrrev_i16_sdwa v1, v219, sext(v1) dst_sel:DWORD dst_unused:UNUSED_PAD src0_sel:DWORD src1_sel:BYTE_0
	s_lshl_b64 s[0:1], s[16:17], 18
	s_lshl_b64 s[8:9], s[8:9], 16
	v_and_b32_e32 v6, 4, v6
	v_and_b32_e32 v7, 24, v7
	v_and_b32_e32 v4, 32, v4
	v_bfe_i32 v1, v1, 0, 16
	s_add_u32 s18, s27, s8
	v_or3_b32 v3, v3, v6, v7
	v_add_lshl_u32 v1, v4, v1, 1
	s_addc_u32 s19, s28, s9
	s_add_i32 s43, s29, 0
	v_lshl_add_u32 v132, v3, 8, v1
	s_add_i32 m0, s43, 0x10000
	v_lshl_add_u32 v134, v5, 10, v1
	global_load_lds_dwordx4 v132, s[18:19]
	s_add_i32 m0, s43, 0x12000
	s_add_u32 s8, s18, 0x8000
	global_load_lds_dwordx4 v128, s[18:19]
	s_addc_u32 s9, s19, 0
	s_add_i32 m0, s43, 0x14000
	s_nop 0
	global_load_lds_dwordx4 v132, s[8:9]
	s_add_i32 m0, s43, 0x16000
	s_add_u32 s20, s25, s0
	s_addc_u32 s21, s26, s1
	s_add_i32 s44, s43, 0x2000
	global_load_lds_dwordx4 v128, s[8:9]
	s_mov_b32 m0, s43
	s_add_u32 s0, s20, 0x20000
	global_load_lds_dwordx4 v134, s[20:21]
	s_mov_b32 m0, s44
	s_addc_u32 s1, s21, 0
	s_add_i32 s50, s43, 0x4000
	global_load_lds_dwordx4 v130, s[20:21]
	s_mov_b32 m0, s50
	s_add_i32 s51, s43, 0x6000
	global_load_lds_dwordx4 v134, s[0:1]
	s_mov_b32 m0, s51
	s_cmp_eq_u32 s6, 1
	global_load_lds_dwordx4 v130, s[0:1]
	s_cselect_b64 s[0:1], -1, 0
	s_cmp_lg_u32 s6, 1
	s_cbranch_scc1 .LBB0_421
	s_barrier
